# prep: hoist tile-invariant loads out of tile loop; scan: batch the 16 state loads per round; s3: batch C/B staging loads; pool-weight LDS fill unrolled; first phase boundary uses xcd barrier; code pla
# speedup vs baseline: 1.0144x; 1.0144x over previous
.LBB0_9:
	v_readlane_b32 s2, v251, 11
	v_writelane_b32 v253, s6, 41
	s_cmp_lg_u32 s6, s2
	s_mov_b64 s[6:7], 0
	s_mov_b64 s[4:5], -1
	v_readlane_b32 s6, v251, 9
	v_readlane_b32 s7, v251, 10
	v_readlane_b32 s2, v253, 41
	s_mov_b64 s[4:5], 0
	s_cmp_gt_i32 s2, s6
	s_mov_b64 s[6:7], 0
	s_cbranch_scc0 .LBB0_64
	s_waitcnt vmcnt(0)
	s_barrier
	s_mov_b64 s[6:7], exec
	v_readlane_b32 s8, v251, 7
	v_readlane_b32 s9, v251, 8
	s_and_b64 s[8:9], s[6:7], s[8:9]
	s_mov_b64 exec, s[8:9]
	s_cbranch_execz .LBB0_63
	v_readlane_b32 s2, v253, 32
	s_waitcnt vmcnt(0) expcnt(0) lgkmcnt(0)
	s_nop 0
	v_mov_b32_e32 v0, s2
	ds_read_b32 v3, v0
	v_readlane_b32 s2, v253, 33
	s_waitcnt lgkmcnt(0)
	v_cmp_ne_u32_e32 vcc, 0, v3
	v_mov_b32_e32 v0, s2
	ds_read_b32 v0, v0
	s_cbranch_vccnz .LBB0_27
	s_mov_b32 s2, 1
	s_branch .LBB0_15

.LBB0_15:
	v_readlane_b32 s10, v253, 1
	s_waitcnt lgkmcnt(0)
	v_readlane_b32 s8, v251, 14
	v_readlane_b32 s9, v251, 15
	s_nop 4
	global_load_dword v0, v1, s[8:9] sc1
	v_readlane_b32 s8, v251, 16
	v_readlane_b32 s9, v251, 17
	s_nop 4
	global_load_dword v2, v1, s[8:9] sc1
	v_readlane_b32 s8, v251, 18
	v_readlane_b32 s9, v251, 19
	s_nop 4
	global_load_dword v3, v1, s[8:9] sc1
	v_readlane_b32 s8, v251, 20
	v_readlane_b32 s9, v251, 21
	s_nop 4
	global_load_dword v4, v1, s[8:9] sc1
	v_readlane_b32 s8, v251, 22
	v_readlane_b32 s9, v251, 23
	s_nop 4
	global_load_dword v5, v1, s[8:9] sc1
	v_readlane_b32 s8, v251, 24
	v_readlane_b32 s9, v251, 25
	s_nop 4
	global_load_dword v6, v1, s[8:9] sc1
	v_readlane_b32 s8, v251, 26
	v_readlane_b32 s9, v251, 27
	s_nop 4
	global_load_dword v7, v1, s[8:9] sc1
	v_readlane_b32 s8, v251, 28
	v_readlane_b32 s9, v251, 29
	s_nop 4
	global_load_dword v8, v1, s[8:9] sc1
	v_readlane_b32 s8, v251, 30
	v_readlane_b32 s9, v251, 31
	s_nop 4
	global_load_dword v9, v1, s[8:9] sc1
	v_readlane_b32 s8, v251, 32
	v_readlane_b32 s9, v251, 33
	s_nop 4
	global_load_dword v10, v1, s[8:9] sc1
	v_readlane_b32 s8, v251, 34
	v_readlane_b32 s9, v251, 35
	s_nop 4
	global_load_dword v11, v1, s[8:9] sc1
	v_readlane_b32 s8, v251, 36
	v_readlane_b32 s9, v251, 37
	s_nop 4
	global_load_dword v12, v1, s[8:9] sc1
	v_readlane_b32 s8, v251, 38
	v_readlane_b32 s9, v251, 39
	s_nop 4
	global_load_dword v13, v1, s[8:9] sc1
	v_readlane_b32 s8, v251, 40
	v_readlane_b32 s9, v251, 41
	s_nop 4
	global_load_dword v14, v1, s[8:9] sc1
	v_readlane_b32 s8, v251, 42
	v_readlane_b32 s9, v251, 43
	s_nop 4
	global_load_dword v15, v1, s[8:9] sc1
	v_readlane_b32 s8, v251, 44
	v_readlane_b32 s9, v251, 45
	s_nop 4
	global_load_dword v16, v1, s[8:9] sc1
	s_mov_b64 s[8:9], -1
	s_waitcnt vmcnt(0)
	v_add_u32_e32 v17, v2, v0
	v_add_u32_e32 v17, v17, v3
	v_add_u32_e32 v17, v17, v4
	v_add_u32_e32 v17, v17, v5
	v_add_u32_e32 v17, v17, v6
	v_add_u32_e32 v17, v17, v7
	v_add_u32_e32 v17, v17, v8
	v_add_u32_e32 v17, v17, v9
	v_add_u32_e32 v17, v17, v10
	v_add_u32_e32 v17, v17, v11
	v_add_u32_e32 v17, v17, v12
	v_add_u32_e32 v17, v17, v13
	v_add_u32_e32 v17, v17, v14
	v_add_u32_e32 v17, v17, v15
	v_add_u32_e32 v17, v17, v16
	v_cmp_eq_u32_e32 vcc, s10, v17
	s_mov_b64 s[10:11], -1
	s_cbranch_vccnz .LBB0_14
	s_and_b32 s8, s2, 0xff
	s_cmp_eq_u32 s8, 0
	s_mov_b64 s[8:9], -1
	s_mov_b64 s[12:13], -1
	s_sleep 1
	s_cbranch_scc0 .LBB0_19
	v_readlane_b32 s8, v251, 12
	v_readlane_b32 s9, v251, 13
	s_nop 4
	global_load_dword v17, v1, s[8:9] sc1
	s_waitcnt vmcnt(0)
	v_cmp_eq_u32_e32 vcc, 0, v17
	s_cbranch_vccnz .LBB0_21
	s_mov_b64 s[12:13], 0
	s_mov_b64 s[8:9], -1

.LBB0_64:
	s_and_b64 vcc, exec, s[4:5]
	s_cbranch_vccz .LBB0_76
.LBB0_76:
	s_and_b64 vcc, exec, s[6:7]
	s_cbranch_vccz .LBB0_78

.LBB0_81:
	s_and_b64 vcc, exec, s[4:5]
	s_cbranch_vccz .LBB0_8
	s_branch .LBB0_701
	s_nop 0
	s_nop 0
	s_nop 0
	s_nop 0
	s_nop 0

.LBB0_143:
	s_or_b64 exec, exec, s[6:7]
	v_add_u32_e32 v36, s4, v104
	v_ashrrev_i32_e32 v37, 31, v36
	v_readlane_b32 s12, v253, 46
	v_lshlrev_b64 v[36:37], 11, v[36:37]
	v_readlane_b32 s13, v253, 47
	v_lshlrev_b32_e32 v0, 4, v102
	v_and_b32_e32 v0, 0xf0, v0
	v_lshl_add_u64 v[36:37], s[12:13], 0, v[36:37]
	v_lshl_add_u64 v[36:37], v[36:37], 0, s[2:3]
	v_lshl_add_u64 v[42:43], v[36:37], 0, v[0:1]
	global_load_dwordx4 v[156:159], v[42:43], off offset:1536
	global_load_dwordx4 v[160:163], v[42:43], off offset:1024
	v_add_u32_e32 v40, 0, v0
	s_movk_i32 s8, 0x110
	v_mad_u64_u32 v[44:45], s[6:7], v104, s8, v[40:41]
	v_lshlrev_b32_e32 v120, 1, v121
	v_add_u32_e32 v93, 0, v120
	v_cmp_lt_i32_e32 vcc, -1, v100
	v_mad_u32_u24 v95, v101, s8, v93
	v_readlane_b32 s14, v253, 48
	v_readlane_b32 s15, v253, 49
	v_mov_b32_e32 v154, v44
	v_add_u32_e32 v36, s4, v106
	v_ashrrev_i32_e32 v37, 31, v36
	v_lshlrev_b64 v[36:37], 11, v[36:37]
	v_lshl_add_u64 v[36:37], s[12:13], 0, v[36:37]
	v_lshl_add_u64 v[36:37], v[36:37], 0, s[2:3]
	v_lshl_add_u64 v[42:43], v[36:37], 0, v[0:1]
	global_load_dwordx4 v[164:167], v[42:43], off offset:1536
	global_load_dwordx4 v[168:171], v[42:43], off offset:1024
	v_mad_u64_u32 v[44:45], s[6:7], v106, s8, v[40:41]
	v_ashrrev_i32_e32 v36, 4, v2
	v_add_u32_e32 v2, s4, v36
	v_ashrrev_i32_e32 v3, 31, v2
	v_lshlrev_b64 v[2:3], 11, v[2:3]
	v_lshl_add_u64 v[2:3], s[12:13], 0, v[2:3]
	v_lshl_add_u64 v[2:3], v[2:3], 0, s[2:3]
	v_lshl_add_u64 v[2:3], v[2:3], 0, v[0:1]
	v_mad_u64_u32 v[42:43], s[6:7], v36, s8, v[40:41]
	global_load_dwordx4 v[172:175], v[2:3], off offset:1536
	global_load_dwordx4 v[176:179], v[2:3], off offset:1024
	v_ashrrev_i32_e32 v36, 4, v91
	v_add_u32_e32 v2, s4, v36
	v_ashrrev_i32_e32 v3, 31, v2
	v_lshlrev_b64 v[2:3], 11, v[2:3]
	v_lshl_add_u64 v[2:3], s[12:13], 0, v[2:3]
	v_lshl_add_u64 v[2:3], v[2:3], 0, s[2:3]
	v_lshl_add_u64 v[2:3], v[2:3], 0, v[0:1]
	v_mad_u64_u32 v[40:41], s[4:5], v36, s8, v[40:41]
	global_load_dwordx4 v[180:183], v[2:3], off offset:1536
	global_load_dwordx4 v[184:187], v[2:3], off offset:1024
	v_mul_lo_u32 v0, v80, s8
	v_add_u32_e32 v81, 0, v0
	v_add_u32_e32 v109, v81, v120
	v_mov_b32_e32 v0, v1
	v_mov_b32_e32 v2, v1
	v_mov_b32_e32 v3, v1
	s_waitcnt vmcnt(7)
	ds_write_b128 v154, v[156:159]
	s_waitcnt vmcnt(6)
	ds_write_b128 v154, v[160:163] offset:34816
	s_waitcnt vmcnt(5)
	ds_write_b128 v44, v[164:167]
	s_waitcnt vmcnt(4)
	ds_write_b128 v44, v[168:171] offset:34816
	s_waitcnt vmcnt(3)
	ds_write_b128 v42, v[172:175]
	s_waitcnt vmcnt(2)
	ds_write_b128 v42, v[176:179] offset:34816
	s_waitcnt vmcnt(1)
	ds_write_b128 v40, v[180:183]
	s_waitcnt vmcnt(0)
	ds_write_b128 v40, v[184:187] offset:34816
	s_nop 0
	s_nop 0
	s_nop 0
	s_nop 0
	s_nop 0
	s_nop 0
	s_nop 0
	s_nop 0
	s_nop 0
	s_nop 0
	s_nop 0
	s_nop 0
	s_nop 0
	s_nop 0
	s_nop 0
	s_waitcnt lgkmcnt(0)
	s_barrier
	ds_read_b128 v[76:79], v109
	v_mov_b64_e32 v[38:39], v[2:3]
	v_mov_b64_e32 v[36:37], v[0:1]
	s_and_saveexec_b64 s[4:5], vcc
	s_cbranch_execz .LBB0_145
	ds_read_b128 v[36:39], v95 offset:34816
	s_waitcnt lgkmcnt(0)
	v_mfma_f32_16x16x32_bf16 v[36:39], v[36:39], v[76:79], 0

.LBB0_303:
	s_nop 0
	v_lshl_add_u64 v[22:23], s[18:19], 0, v[2:3]
	v_add_co_u32_e32 v24, vcc, 0x1f3e0000, v22
	v_lshl_add_u64 v[18:19], s[18:19], 0, v[4:5]
	s_mov_b64 s[10:11], 0x1b3e0000
	v_addc_co_u32_e32 v25, vcc, 0, v23, vcc
	s_mov_b64 s[16:17], 0x40000
	global_load_dword v26, v[24:25], off
	global_load_dword v28, v[24:25], off offset:32
	global_load_dword v30, v[24:25], off offset:64
	global_load_dword v32, v[24:25], off offset:96
	global_load_dword v34, v[24:25], off offset:128
	global_load_dword v36, v[24:25], off offset:160
	global_load_dword v38, v[24:25], off offset:192
	global_load_dword v40, v[24:25], off offset:224
	global_load_dword v22, v[24:25], off offset:256
	global_load_dword v16, v[24:25], off offset:288
	global_load_dword v14, v[24:25], off offset:320
	global_load_dword v12, v[24:25], off offset:352
	global_load_dword v10, v[24:25], off offset:384
	global_load_dword v8, v[24:25], off offset:416
	global_load_dword v6, v[24:25], off offset:448
	global_load_dword v0, v[24:25], off offset:480
	v_lshl_add_u64 v[80:81], v[18:19], 0, s[10:11]
	v_lshl_add_u64 v[82:83], v[80:81], 0, s[16:17]
	v_lshl_add_u64 v[84:85], v[82:83], 0, s[16:17]
	v_lshl_add_u64 v[86:87], v[84:85], 0, s[16:17]
	v_lshl_add_u64 v[88:89], v[86:87], 0, s[16:17]
	v_lshl_add_u64 v[90:91], v[88:89], 0, s[16:17]
	v_lshl_add_u64 v[92:93], v[90:91], 0, s[16:17]
	v_lshl_add_u64 v[94:95], v[92:93], 0, s[16:17]
	v_lshl_add_u64 v[96:97], v[94:95], 0, s[16:17]
	v_lshl_add_u64 v[98:99], v[96:97], 0, s[16:17]
	v_lshl_add_u64 v[100:101], v[98:99], 0, s[16:17]
	v_lshl_add_u64 v[102:103], v[100:101], 0, s[16:17]
	v_lshl_add_u64 v[104:105], v[102:103], 0, s[16:17]
	v_lshl_add_u64 v[106:107], v[104:105], 0, s[16:17]
	v_lshl_add_u64 v[108:109], v[106:107], 0, s[16:17]
	v_lshl_add_u64 v[110:111], v[108:109], 0, s[16:17]
	global_load_dwordx2 v[48:49], v[80:81], off
	global_load_dwordx2 v[50:51], v[82:83], off
	global_load_dwordx2 v[52:53], v[84:85], off
	global_load_dwordx2 v[54:55], v[86:87], off
	global_load_dwordx2 v[56:57], v[88:89], off
	global_load_dwordx2 v[58:59], v[90:91], off
	global_load_dwordx2 v[60:61], v[92:93], off
	global_load_dwordx2 v[62:63], v[94:95], off
	global_load_dwordx2 v[64:65], v[96:97], off
	global_load_dwordx2 v[66:67], v[98:99], off
	global_load_dwordx2 v[68:69], v[100:101], off
	global_load_dwordx2 v[70:71], v[102:103], off
	global_load_dwordx2 v[72:73], v[104:105], off
	global_load_dwordx2 v[74:75], v[106:107], off
	global_load_dwordx2 v[76:77], v[108:109], off
	global_load_dwordx2 v[78:79], v[110:111], off
	s_mov_b64 s[10:11], 0x400000
	v_lshl_add_u64 v[2:3], v[2:3], 0, s[12:13]
	v_lshl_add_u64 v[4:5], v[4:5], 0, s[10:11]
	s_add_i32 s2, s2, 16
	s_cmp_gt_u32 s2, 47
	s_waitcnt vmcnt(15)
	global_store_dwordx2 v[80:81], v[20:21], off
	v_pk_fma_f32 v[20:21], v[20:21], v[26:27], v[48:49] op_sel_hi:[1,0,1]
	s_waitcnt vmcnt(15)
	global_store_dwordx2 v[82:83], v[20:21], off
	v_pk_fma_f32 v[20:21], v[20:21], v[28:29], v[50:51] op_sel_hi:[1,0,1]
	s_waitcnt vmcnt(15)
	global_store_dwordx2 v[84:85], v[20:21], off
	v_pk_fma_f32 v[20:21], v[20:21], v[30:31], v[52:53] op_sel_hi:[1,0,1]
	s_waitcnt vmcnt(15)
	global_store_dwordx2 v[86:87], v[20:21], off
	v_pk_fma_f32 v[20:21], v[20:21], v[32:33], v[54:55] op_sel_hi:[1,0,1]
	s_waitcnt vmcnt(15)
	global_store_dwordx2 v[88:89], v[20:21], off
	v_pk_fma_f32 v[20:21], v[20:21], v[34:35], v[56:57] op_sel_hi:[1,0,1]
	s_waitcnt vmcnt(15)
	global_store_dwordx2 v[90:91], v[20:21], off
	v_pk_fma_f32 v[20:21], v[20:21], v[36:37], v[58:59] op_sel_hi:[1,0,1]
	s_waitcnt vmcnt(15)
	global_store_dwordx2 v[92:93], v[20:21], off
	v_pk_fma_f32 v[20:21], v[20:21], v[38:39], v[60:61] op_sel_hi:[1,0,1]
	s_waitcnt vmcnt(15)
	global_store_dwordx2 v[94:95], v[20:21], off
	v_pk_fma_f32 v[20:21], v[20:21], v[40:41], v[62:63] op_sel_hi:[1,0,1]
	s_waitcnt vmcnt(15)
	global_store_dwordx2 v[96:97], v[20:21], off
	v_pk_fma_f32 v[20:21], v[20:21], v[22:23], v[64:65] op_sel_hi:[1,0,1]
	s_waitcnt vmcnt(15)
	global_store_dwordx2 v[98:99], v[20:21], off
	v_pk_fma_f32 v[20:21], v[20:21], v[16:17], v[66:67] op_sel_hi:[1,0,1]
	s_waitcnt vmcnt(15)
	global_store_dwordx2 v[100:101], v[20:21], off
	v_pk_fma_f32 v[20:21], v[20:21], v[14:15], v[68:69] op_sel_hi:[1,0,1]
	s_waitcnt vmcnt(15)
	global_store_dwordx2 v[102:103], v[20:21], off
	v_pk_fma_f32 v[20:21], v[20:21], v[12:13], v[70:71] op_sel_hi:[1,0,1]
	s_waitcnt vmcnt(15)
	global_store_dwordx2 v[104:105], v[20:21], off
	v_pk_fma_f32 v[20:21], v[20:21], v[10:11], v[72:73] op_sel_hi:[1,0,1]
	s_waitcnt vmcnt(15)
	global_store_dwordx2 v[106:107], v[20:21], off
	v_pk_fma_f32 v[20:21], v[20:21], v[8:9], v[74:75] op_sel_hi:[1,0,1]
	s_waitcnt vmcnt(15)
	global_store_dwordx2 v[108:109], v[20:21], off
	v_pk_fma_f32 v[20:21], v[20:21], v[6:7], v[76:77] op_sel_hi:[1,0,1]
	s_waitcnt vmcnt(15)
	global_store_dwordx2 v[110:111], v[20:21], off
	v_pk_fma_f32 v[20:21], v[20:21], v[0:1], v[78:79] op_sel_hi:[1,0,1]
	s_cbranch_scc0 .LBB0_303
	v_readlane_b32 s10, v253, 63
	v_and_b32_e32 v4, 7, v13
	v_and_b32_e32 v0, 63, v15
	v_add_u32_e32 v2, s10, v17
	v_ashrrev_i32_e32 v3, 31, v2
	v_lshlrev_b64 v[2:3], 9, v[2:3]
	v_lshlrev_b32_e32 v4, 6, v4
	v_or3_b32 v2, v2, v4, v0
	v_readlane_b32 s2, v252, 26
	v_lshlrev_b64 v[2:3], 9, v[2:3]
	v_lshl_add_u64 v[2:3], s[6:7], 0, v[2:3]
	v_add_u32_e32 v7, s2, v7
	s_mov_b32 s2, 0x1ffff
	v_and_b32_e32 v0, 0x1f8, v11
	v_cmp_lt_i32_e32 vcc, s2, v7
	v_readlane_b32 s2, v253, 12
	v_lshl_add_u64 v[2:3], v[2:3], 0, v[0:1]
	s_or_b64 s[8:9], vcc, s[8:9]
	v_add_u32_e32 v9, s2, v9
	v_readlane_b32 s11, v254, 0
	global_store_dwordx2 v[2:3], v[20:21], off
	s_andn2_b64 exec, exec, s[8:9]
	s_cbranch_execnz .LBB0_302

.LBB0_307:
	s_and_b64 vcc, exec, s[4:5]
	s_cbranch_vccz .LBB0_313
	v_readlane_b32 s2, v254, 13
	s_cmp_gt_i32 s2, 1
	s_mov_b64 s[4:5], -1
	s_cbranch_scc0 .LBB0_624
	v_readlane_b32 s2, v254, 13
	s_cmp_lt_i32 s2, 3
	s_cbranch_scc1 .LBB0_597
	v_readlane_b32 s4, v253, 61
	s_lshl_b32 s2, s4, 5
	v_writelane_b32 v254, s2, 18
	v_readlane_b32 s5, v253, 62
	v_readlane_b32 s2, v254, 13
	s_cmp_gt_i32 s2, 3
	s_mov_b64 s[4:5], -1
	s_cbranch_scc0 .LBB0_509
	v_readlane_b32 s4, v252, 33
	v_readlane_b32 s5, v252, 34
	s_andn2_b64 vcc, exec, s[4:5]
	v_readlane_b32 s24, v251, 0
	s_cbranch_vccnz .LBB0_469
	v_readlane_b32 s4, v253, 46
	v_readlane_b32 s5, v253, 47
	s_add_u32 s12, s4, 0x1a406000
	v_readlane_b32 s6, v253, 48
	s_addc_u32 s13, s5, 0
	v_readlane_b32 s7, v253, 49
	s_add_u32 s14, s6, 0x1f3e0000
	v_readlane_b32 s2, v253, 30
	s_addc_u32 s15, s7, 0
	s_mov_b32 s16, s2
	v_readlane_b32 s24, v251, 0
	s_branch .LBB0_316
	s_nop 0

.LBB0_512:
	v_ashrrev_i32_e32 v6, 6, v4
	v_lshrrev_b32_e32 v8, 1, v4
	v_and_b32_e32 v9, 35, v4
	s_mov_b32 s2, 0xfffffc0
	v_and_b32_e32 v7, 16, v0
	v_and_b32_e32 v8, 12, v8
	v_and_or_b32 v6, v6, s2, v9
	v_or3_b32 v6, v6, v7, v8
	v_lshrrev_b32_e32 v7, 5, v4
	v_mul_lo_u32 v6, v6, s10
	v_and_b32_e32 v7, 0x7e, v7
	v_add3_u32 v6, 0, v6, v7
	s_mov_b64 s[8:9], 0x1000
	global_load_dword v148, v[2:3], off
	global_load_dword v149, v[2:3], off offset:2048
	v_lshl_add_u64 v[2:3], v[2:3], 0, s[8:9]
	global_load_dword v150, v[2:3], off
	global_load_dword v151, v[2:3], off offset:2048
	v_lshl_add_u64 v[2:3], v[2:3], 0, s[8:9]
	global_load_dword v152, v[2:3], off
	global_load_dword v153, v[2:3], off offset:2048
	v_lshl_add_u64 v[2:3], v[2:3], 0, s[8:9]
	global_load_dword v154, v[2:3], off
	global_load_dword v155, v[2:3], off offset:2048
	v_lshl_add_u64 v[2:3], v[2:3], 0, s[8:9]
	global_load_dword v156, v[2:3], off
	global_load_dword v157, v[2:3], off offset:2048
	v_lshl_add_u64 v[2:3], v[2:3], 0, s[8:9]
	global_load_dword v158, v[2:3], off
	global_load_dword v159, v[2:3], off offset:2048
	v_lshl_add_u64 v[2:3], v[2:3], 0, s[8:9]
	global_load_dword v160, v[2:3], off
	global_load_dword v161, v[2:3], off offset:2048
	v_lshl_add_u64 v[2:3], v[2:3], 0, s[8:9]
	global_load_dword v162, v[2:3], off
	global_load_dword v163, v[2:3], off offset:2048
	v_lshl_add_u64 v[2:3], v[2:3], 0, s[8:9]
	global_load_dword v164, v[2:3], off
	global_load_dword v165, v[2:3], off offset:2048
	v_lshl_add_u64 v[2:3], v[2:3], 0, s[8:9]
	global_load_dword v166, v[2:3], off
	global_load_dword v167, v[2:3], off offset:2048
	v_lshl_add_u64 v[2:3], v[2:3], 0, s[8:9]
	global_load_dword v168, v[2:3], off
	global_load_dword v169, v[2:3], off offset:2048
	v_lshl_add_u64 v[2:3], v[2:3], 0, s[8:9]
	global_load_dword v170, v[2:3], off
	global_load_dword v171, v[2:3], off offset:2048
	v_lshl_add_u64 v[2:3], v[2:3], 0, s[8:9]
	global_load_dword v172, v[2:3], off
	global_load_dword v173, v[2:3], off offset:2048
	v_lshl_add_u64 v[2:3], v[2:3], 0, s[8:9]
	global_load_dword v174, v[2:3], off
	global_load_dword v175, v[2:3], off offset:2048
	v_lshl_add_u64 v[2:3], v[2:3], 0, s[8:9]
	global_load_dword v176, v[2:3], off
	global_load_dword v177, v[2:3], off offset:2048
	v_lshl_add_u64 v[2:3], v[2:3], 0, s[8:9]
	global_load_dword v178, v[2:3], off
	global_load_dword v179, v[2:3], off offset:2048
	s_waitcnt vmcnt(31)
	v_cvt_pk_bf16_f32 v148, v148, v1
	ds_write_b16 v6, v148
	s_waitcnt vmcnt(30)
	v_cvt_pk_bf16_f32 v149, v149, v1
	ds_write_b16 v6, v149 offset:16
	s_waitcnt vmcnt(29)
	v_cvt_pk_bf16_f32 v150, v150, v1
	ds_write_b16 v6, v150 offset:32
	s_waitcnt vmcnt(28)
	v_cvt_pk_bf16_f32 v151, v151, v1
	ds_write_b16 v6, v151 offset:48
	s_waitcnt vmcnt(27)
	v_cvt_pk_bf16_f32 v152, v152, v1
	ds_write_b16 v6, v152 offset:64
	s_waitcnt vmcnt(26)
	v_cvt_pk_bf16_f32 v153, v153, v1
	ds_write_b16 v6, v153 offset:80
	s_waitcnt vmcnt(25)
	v_cvt_pk_bf16_f32 v154, v154, v1
	ds_write_b16 v6, v154 offset:96
	s_waitcnt vmcnt(24)
	v_cvt_pk_bf16_f32 v155, v155, v1
	ds_write_b16 v6, v155 offset:112
	s_waitcnt vmcnt(23)
	v_cvt_pk_bf16_f32 v156, v156, v1
	ds_write_b16 v6, v156 offset:9216
	s_waitcnt vmcnt(22)
	v_cvt_pk_bf16_f32 v157, v157, v1
	ds_write_b16 v6, v157 offset:9232
	s_waitcnt vmcnt(21)
	v_cvt_pk_bf16_f32 v158, v158, v1
	ds_write_b16 v6, v158 offset:9248
	s_waitcnt vmcnt(20)
	v_cvt_pk_bf16_f32 v159, v159, v1
	ds_write_b16 v6, v159 offset:9264
	s_waitcnt vmcnt(19)
	v_cvt_pk_bf16_f32 v160, v160, v1
	ds_write_b16 v6, v160 offset:9280
	s_waitcnt vmcnt(18)
	v_cvt_pk_bf16_f32 v161, v161, v1
	ds_write_b16 v6, v161 offset:9296
	s_waitcnt vmcnt(17)
	v_cvt_pk_bf16_f32 v162, v162, v1
	ds_write_b16 v6, v162 offset:9312
	s_waitcnt vmcnt(16)
	v_cvt_pk_bf16_f32 v163, v163, v1
	ds_write_b16 v6, v163 offset:9328
	s_waitcnt vmcnt(15)
	v_cvt_pk_bf16_f32 v164, v164, v1
	ds_write_b16 v6, v164 offset:18432
	s_waitcnt vmcnt(14)
	v_cvt_pk_bf16_f32 v165, v165, v1
	ds_write_b16 v6, v165 offset:18448
	s_waitcnt vmcnt(13)
	v_cvt_pk_bf16_f32 v166, v166, v1
	ds_write_b16 v6, v166 offset:18464
	s_waitcnt vmcnt(12)
	v_cvt_pk_bf16_f32 v167, v167, v1
	ds_write_b16 v6, v167 offset:18480
	s_waitcnt vmcnt(11)
	v_cvt_pk_bf16_f32 v168, v168, v1
	ds_write_b16 v6, v168 offset:18496
	s_waitcnt vmcnt(10)
	v_cvt_pk_bf16_f32 v169, v169, v1
	ds_write_b16 v6, v169 offset:18512
	s_waitcnt vmcnt(9)
	v_cvt_pk_bf16_f32 v170, v170, v1
	ds_write_b16 v6, v170 offset:18528
	s_waitcnt vmcnt(8)
	v_cvt_pk_bf16_f32 v171, v171, v1
	ds_write_b16 v6, v171 offset:18544
	s_waitcnt vmcnt(7)
	v_cvt_pk_bf16_f32 v172, v172, v1
	ds_write_b16 v6, v172 offset:27648
	s_waitcnt vmcnt(6)
	v_cvt_pk_bf16_f32 v173, v173, v1
	ds_write_b16 v6, v173 offset:27664
	s_waitcnt vmcnt(5)
	v_cvt_pk_bf16_f32 v174, v174, v1
	ds_write_b16 v6, v174 offset:27680
	s_waitcnt vmcnt(4)
	v_cvt_pk_bf16_f32 v175, v175, v1
	ds_write_b16 v6, v175 offset:27696
	s_waitcnt vmcnt(3)
	v_cvt_pk_bf16_f32 v176, v176, v1
	ds_write_b16 v6, v176 offset:27712
	s_waitcnt vmcnt(2)
	v_cvt_pk_bf16_f32 v177, v177, v1
	ds_write_b16 v6, v177 offset:27728
	s_waitcnt vmcnt(1)
	v_cvt_pk_bf16_f32 v178, v178, v1
	ds_write_b16 v6, v178 offset:27744
	s_waitcnt vmcnt(0)
	v_cvt_pk_bf16_f32 v179, v179, v1
	ds_write_b16 v6, v179 offset:27760

.LBB0_515:
	s_or_b64 exec, exec, s[4:5]
	v_readlane_b32 s6, v253, 61
	v_readlane_b32 s7, v253, 62
	v_readlane_b32 s8, v253, 46
	s_lshl_b64 s[4:5], s[6:7], 15
	v_readlane_b32 s10, v253, 48
	v_readlane_b32 s11, v253, 49
	s_add_u32 s2, s10, s4
	s_addc_u32 s4, s11, s5
	s_add_u32 s16, s2, 0x1f6e4000
	s_addc_u32 s17, s4, 0
	v_readlane_b32 s4, v252, 52
	s_lshl_b32 s18, s6, 8
	s_lshl_b32 s20, s6, 10
	v_readlane_b32 s5, v252, 53
	s_ashr_i32 s19, s18, 31
	s_ashr_i32 s21, s20, 31
	s_andn2_b64 vcc, exec, s[4:5]
	v_readlane_b32 s9, v253, 47
	s_waitcnt lgkmcnt(0)
	s_barrier
	s_cbranch_vccnz .LBB0_570
	v_readlane_b32 s4, v253, 63
	s_mov_b32 s6, s4
	v_readlane_b32 s28, v253, 46
	s_mov_b32 s2, s6
	v_and_b32_e32 v83, 15, v82
	v_readlane_b32 s29, v253, 47
	v_readlane_b32 s30, v253, 48
	v_readlane_b32 s31, v253, 49
	v_readlane_b32 s5, v254, 0
	v_writelane_b32 v253, s2, 63
	v_lshlrev_b32_e32 v87, 3, v82
	v_lshlrev_b32_e32 v0, 11, v83
	v_writelane_b32 v254, s3, 0
	v_and_b32_e32 v11, 0xf8, v87
	v_readlane_b32 s30, v254, 1
	v_lshl_add_u64 v[4:5], s[16:17], 0, v[0:1]
	v_lshlrev_b32_e32 v0, 1, v11
	v_readlane_b32 s31, v254, 2
	v_ashrrev_i32_e32 v3, 6, v82
	v_lshlrev_b32_e32 v15, 5, v83
	v_lshl_add_u64 v[84:85], s[30:31], 0, v[0:1]
	v_lshlrev_b32_e32 v0, 4, v82
	v_and_b32_e32 v8, 0x100, v0
	v_lshlrev_b32_e32 v0, 9, v3
	v_readlane_b32 s8, v253, 36
	s_add_u32 s22, s28, 0x1112e000
	v_bfe_u32 v7, v82, 4, 2
	v_add3_u32 v16, s8, v0, v15
	v_and_b32_e32 v15, 7, v82
	v_and_b32_e32 v0, 0x3ffffff8, v82
	v_lshlrev_b32_e32 v17, 2, v0
	v_lshlrev_b32_e32 v0, 2, v15
	v_add3_u32 v130, s8, v17, v0
	v_readlane_b32 s8, v253, 58
	s_addc_u32 s23, s29, 0
	s_ashr_i32 s7, s4, 31
	s_or_b32 s4, s4, 1
	v_or_b32_e32 v90, s8, v15
	v_readlane_b32 s8, v254, 11
	s_ashr_i32 s5, s4, 31
	v_lshlrev_b32_e32 v9, 3, v7
	v_ashrrev_i32_e32 v14, 7, v82
	v_readlane_b32 s9, v254, 12
	s_lshl_b64 s[26:27], s[4:5], 12
	s_or_b32 s4, s6, 2
	v_lshl_or_b32 v2, v3, 7, v9
	v_lshl_add_u64 v[92:93], s[8:9], 0, v[0:1]
	v_lshlrev_b32_e32 v0, 5, v3
	v_lshlrev_b32_e32 v3, 6, v14
	v_readlane_b32 s15, v253, 37
	s_ashr_i32 s5, s4, 31
	v_lshlrev_b32_e32 v126, 2, v14
	v_mov_b32_e32 v14, s15
	s_movk_i32 s10, 0x210
	v_and_or_b32 v18, v0, 32, v3
	s_lshl_b64 s[38:39], s[4:5], 12
	s_or_b32 s4, s6, 3
	v_and_b32_e32 v13, 31, v82
	v_mad_u32_u24 v14, v83, s10, v14
	v_or_b32_e32 v94, v18, v9
	v_readlane_b32 s10, v254, 3
	s_ashr_i32 s5, s4, 31
	v_and_b32_e32 v6, 24, v87
	v_ashrrev_i32_e32 v95, 31, v94
	v_readlane_b32 s11, v254, 4
	v_cmp_gt_u32_e32 vcc, 16, v13
	v_mov_b32_e32 v0, 0x3e000000
	v_ashrrev_i32_e32 v3, 31, v2
	s_lshl_b64 s[40:41], s[4:5], 12
	v_cmp_gt_u32_e64 s[4:5], 2, v7
	v_lshlrev_b32_e32 v7, 4, v7
	v_and_b32_e32 v15, 0xffffff80, v82
	v_lshl_add_u64 v[96:97], v[94:95], 1, s[10:11]
	v_cndmask_b32_e32 v98, 1.0, v0, vcc
	s_mov_b32 s10, 0x1fffffe0
	v_lshlrev_b32_e32 v0, 2, v6
	v_lshlrev_b64 v[2:3], 1, v[2:3]
	v_and_b32_e32 v12, 0x3f8, v87
	v_add3_u32 v131, v14, v15, v7
	v_and_or_b32 v9, v82, s10, v6
	v_lshl_add_u64 v[14:15], s[28:29], 0, v[0:1]
	s_mov_b64 s[10:11], 0x812e000
	v_lshl_add_u64 v[106:107], v[4:5], 0, v[2:3]
	v_add_u32_e32 v4, 0x200, v82
	s_add_i32 s2, 0, 0x10000
	v_lshl_add_u64 v[100:101], v[14:15], 0, s[10:11]
	v_lshlrev_b32_e32 v14, 2, v12
	v_mov_b32_e32 v15, v1
	v_ashrrev_i32_e32 v132, 5, v4
	v_lshlrev_b32_e32 v4, 5, v4
	v_lshl_add_u32 v11, v11, 2, s2
	v_lshl_add_u64 v[14:15], s[28:29], 0, v[14:15]
	s_mov_b64 s[10:11], 0x1a12e000
	v_and_b32_e32 v4, 0xfffffc00, v4
	v_lshlrev_b32_e32 v0, 1, v12
	v_lshl_add_u64 v[104:105], v[14:15], 0, s[10:11]
	v_and_b32_e32 v14, 0xff, v82
	v_lshlrev_b32_e32 v5, 5, v82
	v_add_u32_e32 v134, v11, v4
	v_bfe_u32 v4, v82, 6, 2
	v_lshl_add_u64 v[102:103], s[28:29], 0, v[0:1]
	v_and_b32_e32 v5, 0xfffffc00, v5
	v_lshlrev_b32_e64 v135, v4, 2
	v_or_b32_e32 v4, v18, v83
	v_lshl_add_u64 v[110:111], s[30:31], 0, v[0:1]
	v_lshlrev_b32_e32 v0, 2, v14
	s_lshl_b64 s[24:25], s[6:7], 12
	v_bfe_u32 v86, v82, 2, 2
	s_add_i32 s6, 0, 0x1cc00
	v_add_u32_e32 v133, v11, v5
	v_lshl_add_u32 v136, v14, 1, s15
	v_mul_lo_u32 v4, v4, s14
	v_lshlrev_b32_e32 v5, 3, v9
	v_readlane_b32 s14, v253, 44
	v_add_u32_e32 v140, s2, v0
	v_readlane_b32 s2, v253, 38
	v_lshlrev_b32_e32 v10, 6, v86
	v_lshl_add_u32 v128, v13, 2, s6
	s_movk_i32 s6, 0x80
	s_movk_i32 s8, 0x1000
	v_add_u32_e32 v17, 0, v7
	v_cmp_lt_u32_e32 vcc, 15, v13
	s_movk_i32 s10, 0x3e0
	s_movk_i32 s12, 0x1e0
	v_readlane_b32 s15, v253, 45
	v_add_u32_e32 v141, s2, v0
	v_add_u32_e32 v0, 0, v5
	v_ashrrev_i32_e32 v89, 5, v82
	v_lshlrev_b32_e32 v88, 3, v13
	v_add_u32_e32 v127, -3, v126
	v_cmp_gt_i32_e64 s[6:7], s6, v82
	v_ashrrev_i32_e32 v129, 3, v82
	v_ashrrev_i32_e32 v91, 31, v90
	v_cmp_gt_i32_e64 s[8:9], s8, v82
	v_cmp_gt_i32_e64 s[10:11], s10, v82
	v_cmp_gt_i32_e64 s[12:13], s12, v82
	v_or_b32_e32 v137, 1, v126
	v_or_b32_e32 v138, 2, v126
	v_or_b32_e32 v139, 3, v126
	v_mov_b32_e32 v99, v98
	v_lshl_add_u64 v[108:109], s[14:15], 0, v[2:3]
	v_lshlrev_b32_e32 v112, 1, v8
	v_lshlrev_b32_e32 v114, 1, v10
	v_lshlrev_b32_e32 v116, 1, v6
	v_add_u32_e32 v142, v16, v7
	v_lshlrev_b32_e32 v118, 2, v14
	v_add_u32_e32 v143, v17, v4
	v_add_u32_e32 v144, 0x1bc00, v0
	s_xor_b64 s[42:43], vcc, -1
	v_lshlrev_b32_e32 v120, 2, v12
	v_readlane_b32 s98, v253, 42
	v_readlane_b32 s99, v253, 43
	v_mov_b32_e32 v218, v120
	v_mov_b32_e32 v219, v1
	s_load_dwordx2 s[100:101], s[98:99], 0x78
	s_lshl_b64 s[14:15], s[20:21], 2
	s_waitcnt lgkmcnt(0)
	v_lshl_add_u64 v[218:219], s[100:101], 0, v[218:219]
	s_load_dwordx2 s[100:101], s[98:99], 0x80
	v_lshl_add_u64 v[220:221], v[218:219], 0, s[24:25]
	global_load_dwordx4 v[156:159], v[220:221], off offset:16
	global_load_dwordx4 v[160:163], v[220:221], off
	v_lshl_add_u64 v[220:221], v[218:219], 0, s[26:27]
	global_load_dwordx4 v[164:167], v[220:221], off offset:16
	global_load_dwordx4 v[168:171], v[220:221], off
	v_lshl_add_u64 v[220:221], v[218:219], 0, s[38:39]
	global_load_dwordx4 v[172:175], v[220:221], off offset:16
	global_load_dwordx4 v[176:179], v[220:221], off
	v_lshl_add_u64 v[220:221], v[218:219], 0, s[40:41]
	global_load_dwordx4 v[180:183], v[220:221], off offset:16
	global_load_dwordx4 v[184:187], v[220:221], off
	s_waitcnt lgkmcnt(0)
	s_add_u32 s14, s100, s14
	s_addc_u32 s15, s101, s15
	s_load_dwordx2 s[100:101], s[98:99], 0x70
	s_nop 0
	global_load_dwordx4 v[148:151], v120, s[14:15] offset:16
	global_load_dwordx4 v[152:155], v120, s[14:15]
	s_lshl_b64 s[14:15], s[18:19], 2
	s_waitcnt lgkmcnt(0)
	s_add_u32 s14, s100, s14
	s_addc_u32 s15, s101, s15
	s_load_dwordx2 s[100:101], s[98:99], 0x88
	v_lshl_add_u64 v[220:221], v[94:95], 2, s[14:15]
	global_load_dwordx4 v[188:191], v[220:221], off offset:16
	global_load_dwordx4 v[196:199], v[220:221], off
	s_waitcnt lgkmcnt(0)
	v_lshl_add_u64 v[220:221], v[90:91], 2, s[100:101]
	global_load_dword v192, v[220:221], off
	s_waitcnt vmcnt(0)
	v_readlane_b32 s2, v252, 50
	s_branch .LBB0_518
	s_nop 0
	s_nop 0
	s_nop 0
	s_nop 0
	s_nop 0
	s_nop 0
	s_nop 0
	s_nop 0
	s_nop 0
	s_nop 0
	s_nop 0
	s_nop 0
	s_nop 0
	s_nop 0
	s_nop 0
	s_nop 0
	s_nop 0

.LBB0_543:
	s_or_b64 exec, exec, s[14:15]
	v_add_u32_e32 v50, s44, v89
	ds_read_b32 v0, v128
	v_cvt_f32_i32_e32 v42, v50
	s_waitcnt lgkmcnt(0)
	v_mul_f32_e32 v0, v0, v42
	v_mul_f32_e32 v42, 0.15915494, v0
	v_rndne_f32_e32 v42, v42
	v_fmac_f32_e32 v0, 0xc0c90fdb, v42
	v_fmac_f32_e32 v0, 0x343bbd2e, v42
	v_mul_f32_e32 v0, 0.15915494, v0
	v_sin_f32_e32 v43, v0
	v_cos_f32_e32 v42, v0
	v_add_u32_e32 v0, 0, v87
	v_add_u32_e32 v0, 0x1bc00, v0
	ds_write_b64 v0, v[42:43]
	s_waitcnt lgkmcnt(0)
	s_barrier
	s_and_saveexec_b64 s[14:15], s[6:7]
	s_cbranch_execz .LBB0_547
	ds_read2st64_b32 v[42:43], v130 offset1:2
	v_readlane_b32 s28, v253, 50
	v_readlane_b32 s29, v253, 51
	s_waitcnt lgkmcnt(0)
	v_add_f32_e32 v0, 0, v42
	v_add_f32_e32 v0, v0, v43
	ds_read2st64_b32 v[42:43], v130 offset0:4 offset1:6
	s_waitcnt lgkmcnt(0)
	v_add_f32_e32 v0, v0, v42
	v_add_f32_e32 v0, v0, v43
	ds_read2st64_b32 v[42:43], v130 offset0:8 offset1:10
	s_waitcnt lgkmcnt(0)
	v_add_f32_e32 v0, v0, v42
	v_add_f32_e32 v0, v0, v43
	ds_read2st64_b32 v[42:43], v130 offset0:12 offset1:14
	s_waitcnt lgkmcnt(0)
	v_add_f32_e32 v0, v0, v42
	v_add_u32_e32 v42, s33, v129
	v_add_f32_e32 v51, v0, v43
	v_ashrrev_i32_e32 v43, 31, v42
	v_lshlrev_b64 v[44:45], 6, v[42:43]
	v_lshl_add_u64 v[48:49], s[28:29], 0, v[44:45]
	global_load_dwordx4 v[44:47], v[48:49], off offset:32
	global_load_dwordx4 v[52:55], v[48:49], off offset:16
	global_load_dwordx4 v[56:59], v[48:49], off
	global_load_dwordx4 v[60:63], v[48:49], off offset:48
	s_mov_b32 s28, 0x800000
	s_waitcnt vmcnt(3)
	v_mov_b32_e32 v0, v45
	s_waitcnt vmcnt(2)
	v_mov_b32_e32 v64, v53
	s_waitcnt vmcnt(1)
	v_mov_b32_e32 v48, v57
	v_mov_b32_e32 v49, v58
	v_mov_b32_e32 v65, v54
	v_mov_b32_e32 v57, v59
	v_mov_b32_e32 v53, v55
	v_pk_add_f32 v[48:49], v[48:49], v[56:57]
	v_pk_add_f32 v[52:53], v[64:65], v[52:53]
	v_pk_add_f32 v[44:45], v[44:45], v[0:1]
	v_mov_b32_e32 v0, v47
	v_pk_add_f32 v[48:49], v[48:49], v[48:49] op_sel:[0,1] op_sel_hi:[1,0]
	v_pk_add_f32 v[52:53], v[52:53], v[52:53] op_sel:[0,1] op_sel_hi:[1,0]
	v_pk_add_f32 v[46:47], v[46:47], v[0:1]
	s_waitcnt vmcnt(0)
	v_mov_b32_e32 v49, v60
	v_mov_b32_e32 v53, v61
	v_mov_b32_e32 v45, v62
	v_mov_b32_e32 v47, v63
	v_pk_add_f32 v[48:49], v[48:49], v[52:53]
	v_pk_add_f32 v[44:45], v[44:45], v[46:47]
	s_nop 0
	v_pk_add_f32 v[44:45], v[48:49], v[44:45]
	s_nop 0
	v_add_f32_e32 v0, v44, v45
	v_fmamk_f32 v0, v0, 0x3a800000, v241
	v_cmp_gt_f32_e32 vcc, s28, v0
	v_mul_f32_e32 v44, 0x4b800000, v0
	v_readlane_b32 s28, v253, 42
	v_cndmask_b32_e32 v0, v0, v44, vcc
	v_readlane_b32 s29, v253, 43
	v_rsq_f32_e32 v0, v0
	s_nop 0
	v_mul_f32_e32 v44, 0x45800000, v0
	v_cndmask_b32_e32 v46, v0, v44, vcc
	v_mov_b32_e32 v0, v192
	s_mov_b32 s28, 0x41a00000
	v_fmac_f32_e32 v0, v51, v46
	v_cmp_nlt_f32_e32 vcc, s28, v0
	s_and_saveexec_b64 s[28:29], vcc
	s_cbranch_execz .LBB0_546
	v_mul_f32_e32 v0, 0x3fb8aa3b, v0
	v_exp_f32_e32 v0, v0
	s_mov_b32 s30, 0x3f2aaaab
	v_add_f32_e32 v46, 1.0, v0
	v_frexp_mant_f32_e32 v48, v46
	v_cvt_f64_f32_e32 v[44:45], v46
	v_frexp_exp_i32_f64_e32 v44, v[44:45]
	v_cmp_gt_f32_e32 vcc, s30, v48
	v_add_f32_e32 v47, -1.0, v46
	v_sub_f32_e32 v49, v47, v46
	v_subbrev_co_u32_e32 v51, vcc, 0, v44, vcc
	v_sub_u32_e32 v44, 0, v51
	v_sub_f32_e32 v47, v0, v47
	v_add_f32_e32 v49, 1.0, v49
	v_ldexp_f32 v45, v46, v44
	v_add_f32_e32 v47, v47, v49
	v_add_f32_e32 v46, -1.0, v45
	v_add_f32_e32 v48, 1.0, v45
	v_ldexp_f32 v44, v47, v44
	v_add_f32_e32 v47, 1.0, v46
	v_add_f32_e32 v49, -1.0, v48
	v_sub_f32_e32 v47, v45, v47
	v_sub_f32_e32 v45, v45, v49
	v_add_f32_e32 v47, v44, v47
	v_add_f32_e32 v44, v44, v45
	v_add_f32_e32 v54, v48, v44
	v_rcp_f32_e32 v56, v54
	v_sub_f32_e32 v45, v54, v48
	v_sub_f32_e32 v55, v44, v45
	v_add_f32_e32 v45, v46, v47
	v_mul_f32_e32 v58, v45, v56
	v_sub_f32_e32 v44, v45, v46
	v_mul_f32_e32 v46, v54, v58
	v_fma_f32 v48, v58, v54, -v46
	v_fmac_f32_e32 v48, v58, v55
	v_sub_f32_e32 v57, v47, v44
	v_add_f32_e32 v44, v46, v48
	v_sub_f32_e32 v47, v45, v44
	v_pk_add_f32 v[52:53], v[44:45], v[46:47] neg_lo:[0,1] neg_hi:[0,1]
	v_mov_b32_e32 v49, v44
	v_pk_add_f32 v[44:45], v[52:53], v[48:49] neg_lo:[0,1] neg_hi:[0,1]
	s_mov_b32 s30, 0x3f317218
	v_add_f32_e32 v45, v57, v45
	v_add_f32_e32 v44, v44, v45
	v_add_f32_e32 v45, v47, v44
	v_mul_f32_e32 v57, v56, v45
	v_mul_f32_e32 v46, v54, v57
	v_fma_f32 v48, v57, v54, -v46
	v_fmac_f32_e32 v48, v57, v55
	v_sub_f32_e32 v47, v47, v45
	v_add_f32_e32 v54, v44, v47
	v_add_f32_e32 v44, v46, v48
	v_sub_f32_e32 v47, v45, v44
	v_pk_add_f32 v[52:53], v[44:45], v[46:47] neg_lo:[0,1] neg_hi:[0,1]
	v_mov_b32_e32 v49, v44
	v_pk_add_f32 v[44:45], v[52:53], v[48:49] neg_lo:[0,1] neg_hi:[0,1]
	s_nop 0
	v_add_f32_e32 v45, v54, v45
	v_add_f32_e32 v44, v44, v45
	v_add_f32_e32 v45, v58, v57
	v_add_f32_e32 v44, v47, v44
	v_sub_f32_e32 v46, v45, v58
	v_mul_f32_e32 v44, v56, v44
	v_sub_f32_e32 v46, v57, v46
	v_add_f32_e32 v46, v46, v44
	v_add_f32_e32 v48, v45, v46
	v_mul_f32_e32 v49, v48, v48
	v_mov_b32_e32 v44, 0x3ecc95a3
	v_fmamk_f32 v44, v49, 0x3e9b6dac, v44
	v_fmaak_f32 v195, v49, v44, 0x3f2aaada
	v_cvt_f32_i32_e32 v44, v51
	v_sub_f32_e32 v45, v48, v45
	v_sub_f32_e32 v45, v46, v45
	v_ldexp_f32 v51, v45, 1
	v_mul_f32_e32 v45, v48, v49
	v_ldexp_f32 v47, v48, 1
	v_pk_mul_f32 v[48:49], v[44:45], v[194:195]
	s_nop 0
	v_fma_f32 v46, v44, s30, -v48
	v_fmac_f32_e32 v46, 0xb102e308, v44
	v_pk_add_f32 v[44:45], v[48:49], v[46:47]
	v_mov_b32_e32 v52, v48
	v_sub_f32_e32 v47, v45, v47
	v_sub_f32_e32 v47, v49, v47
	v_add_f32_e32 v53, v51, v47
	v_pk_add_f32 v[48:49], v[44:45], v[48:49] neg_lo:[0,1] neg_hi:[0,1]
	v_pk_add_f32 v[54:55], v[44:45], v[52:53]
	v_mov_b32_e32 v47, v44
	v_mov_b32_e32 v49, v55
	v_pk_add_f32 v[56:57], v[46:47], v[48:49] neg_lo:[0,1] neg_hi:[0,1]
	v_pk_add_f32 v[46:47], v[46:47], v[48:49]
	v_mov_b32_e32 v52, v53
	v_pk_add_f32 v[48:49], v[46:47], v[44:45] op_sel:[1,0] op_sel_hi:[0,1] neg_lo:[0,1] neg_hi:[0,1]
	v_pk_add_f32 v[58:59], v[54:55], v[48:49] op_sel_hi:[1,0] neg_lo:[0,1] neg_hi:[0,1]
	v_mov_b32_e32 v54, v55
	v_mov_b32_e32 v55, v47
	v_pk_mov_b32 v[48:49], v[44:45], v[48:49] op_sel:[1,0]
	v_mov_b32_e32 v53, v44
	v_pk_add_f32 v[48:49], v[54:55], v[48:49] neg_lo:[0,1] neg_hi:[0,1]
	v_mov_b32_e32 v58, v56
	v_pk_add_f32 v[44:45], v[52:53], v[48:49] neg_lo:[0,1] neg_hi:[0,1]
	v_mov_b32_e32 v57, v47
	v_pk_add_f32 v[48:49], v[58:59], v[44:45]
	s_mov_b32 s30, 0x7f800000
	v_pk_add_f32 v[52:53], v[48:49], v[48:49] op_sel:[0,1] op_sel_hi:[1,0]
	v_cmp_neq_f32_e32 vcc, s30, v0
	v_pk_add_f32 v[46:47], v[46:47], v[52:53] op_sel:[1,0] op_sel_hi:[0,1]
	v_mov_b32_e32 v49, v46
	v_pk_add_f32 v[54:55], v[48:49], v[56:57] neg_lo:[0,1] neg_hi:[0,1]
	v_mov_b32_e32 v45, v52
	v_sub_f32_e32 v47, v48, v54
	v_pk_add_f32 v[44:45], v[44:45], v[54:55] neg_lo:[0,1] neg_hi:[0,1]
	v_sub_f32_e32 v47, v56, v47
	v_add_f32_e32 v44, v44, v47
	v_add_f32_e32 v44, v44, v45
	v_add_f32_e32 v44, v46, v44
	v_mov_b32_e32 v45, 0x7f800000
	v_cndmask_b32_e32 v44, v45, v44, vcc
	v_cmp_ngt_f32_e32 vcc, -1.0, v0
	s_mov_b32 s30, 0x33800000
	s_nop 0
	v_cndmask_b32_e32 v44, v248, v44, vcc
	v_cmp_neq_f32_e32 vcc, -1.0, v0
	s_nop 1
	v_cndmask_b32_e32 v44, v244, v44, vcc
	v_cmp_lt_f32_e64 vcc, |v0|, s30
	s_nop 1
	v_cndmask_b32_e32 v0, v44, v0, vcc

.LBB0_554:
	s_or_b64 exec, exec, s[14:15]
	s_waitcnt lgkmcnt(0)
	s_barrier
	ds_read_b128 v[42:45], v143
	ds_read_b128 v[46:49], v131
	ds_read_b128 v[52:55], v143 offset:64
	ds_read_b128 v[56:59], v131 offset:64
	s_waitcnt lgkmcnt(2)
	v_mfma_f32_16x16x32_bf16 v[42:45], v[42:45], v[46:49], 0
	s_waitcnt lgkmcnt(0)
	v_mfma_f32_16x16x32_bf16 v[42:45], v[52:55], v[56:59], v[42:45]
	ds_read_b128 v[52:55], v143 offset:2304
	s_waitcnt vmcnt(1)
	v_lshlrev_b32_e32 v60, 16, v41
	s_waitcnt lgkmcnt(0)
	v_mfma_f32_16x16x32_bf16 v[46:49], v[52:55], v[46:49], 0
	ds_read_b128 v[52:55], v143 offset:2368
	v_and_b32_e32 v61, 0xffff0000, v41
	s_waitcnt vmcnt(0)
	v_lshlrev_b32_e32 v62, 16, v34
	v_and_b32_e32 v63, 0xffff0000, v34
	s_waitcnt lgkmcnt(0)
	v_mfma_f32_16x16x32_bf16 v[46:49], v[52:55], v[56:59], v[46:49]
	v_mov_b64_e32 v[52:53], v[188:189]
	v_mov_b64_e32 v[54:55], v[190:191]
	v_mov_b64_e32 v[56:57], v[196:197]
	v_mov_b64_e32 v[58:59], v[198:199]
	v_lshlrev_b32_e32 v64, 16, v35
	v_and_b32_e32 v65, 0xffff0000, v35
	v_lshlrev_b32_e32 v66, 16, v36
	v_and_b32_e32 v67, 0xffff0000, v36
	v_lshlrev_b32_e32 v68, 16, v37
	v_and_b32_e32 v69, 0xffff0000, v37
	s_movk_i32 s14, 0x1800
	v_cmp_gt_i32_e32 vcc, s14, v50
	s_or_b64 s[14:15], s[42:43], vcc
	v_mul_f32_e32 v0, v42, v56
	v_mul_f32_e32 v42, v43, v57
	v_cvt_pk_bf16_f32 v42, v0, v42
	v_mul_f32_e32 v0, v44, v58
	v_mul_f32_e32 v43, v45, v59
	v_cvt_pk_bf16_f32 v43, v0, v43
	v_mul_f32_e32 v0, v46, v52
	v_mul_f32_e32 v44, v47, v53
	v_mul_f32_e32 v45, v49, v55
	v_lshl_add_u64 v[46:47], v[96:97], 0, v[124:125]
	v_cvt_pk_bf16_f32 v44, v0, v44
	v_mul_f32_e32 v0, v48, v54
	v_cvt_pk_bf16_f32 v45, v0, v45
	global_store_dwordx4 v[46:47], v[42:45], off
	v_lshlrev_b32_e32 v58, 16, v40
	v_and_b32_e32 v59, 0xffff0000, v40
	ds_read_b128 v[34:37], v144
	ds_read_b128 v[40:43], v144 offset:16
	ds_read_b128 v[46:49], v144 offset:32
	ds_read_b128 v[52:55], v144 offset:48
	v_lshlrev_b32_e32 v44, 16, v38
	s_waitcnt lgkmcnt(3)
	v_mov_b32_e32 v71, v36
	v_mov_b32_e32 v36, v35
	v_and_b32_e32 v45, 0xffff0000, v38
	v_mov_b32_e32 v70, v34
	v_pk_mul_f32 v[34:35], v[36:37], v[62:63]
	v_lshlrev_b32_e32 v56, 16, v39
	v_pk_fma_f32 v[34:35], v[70:71], v[44:45], v[34:35] neg_lo:[0,0,1] neg_hi:[0,0,1]
	v_and_b32_e32 v57, 0xffff0000, v39
	v_pk_mul_f32 v[38:39], v[98:99], v[34:35]
	v_pk_mul_f32 v[34:35], v[36:37], v[44:45]
	s_waitcnt lgkmcnt(2)
	v_mov_b32_e32 v37, v42
	v_mov_b32_e32 v42, v41
	v_mov_b32_e32 v36, v40
	v_pk_mul_f32 v[40:41], v[42:43], v[64:65]
	v_pk_mul_f32 v[42:43], v[42:43], v[56:57]
	v_pk_fma_f32 v[40:41], v[36:37], v[56:57], v[40:41] neg_lo:[0,0,1] neg_hi:[0,0,1]
	v_pk_fma_f32 v[36:37], v[36:37], v[64:65], v[42:43]
	s_waitcnt lgkmcnt(1)
	v_mov_b32_e32 v43, v48
	v_mov_b32_e32 v48, v47
	v_mov_b32_e32 v42, v46
	v_pk_mul_f32 v[44:45], v[48:49], v[66:67]
	v_pk_fma_f32 v[34:35], v[70:71], v[62:63], v[34:35]
	v_pk_fma_f32 v[44:45], v[42:43], v[58:59], v[44:45] neg_lo:[0,0,1] neg_hi:[0,0,1]
	v_pk_mul_f32 v[34:35], v[98:99], v[34:35]
	v_pk_mul_f32 v[46:47], v[98:99], v[44:45]
	v_pk_mul_f32 v[44:45], v[48:49], v[58:59]
	v_pk_mul_f32 v[40:41], v[98:99], v[40:41]
	v_pk_fma_f32 v[42:43], v[42:43], v[66:67], v[44:45]
	s_waitcnt lgkmcnt(0)
	v_mov_b32_e32 v45, v54
	v_mov_b32_e32 v54, v53
	v_mov_b32_e32 v44, v52
	v_pk_mul_f32 v[48:49], v[54:55], v[68:69]
	v_pk_mul_f32 v[52:53], v[54:55], v[60:61]
	v_pk_fma_f32 v[48:49], v[44:45], v[60:61], v[48:49] neg_lo:[0,0,1] neg_hi:[0,0,1]
	v_pk_fma_f32 v[44:45], v[44:45], v[68:69], v[52:53]
	v_pk_mul_f32 v[36:37], v[98:99], v[36:37]
	v_pk_mul_f32 v[42:43], v[98:99], v[42:43]
	v_pk_mul_f32 v[48:49], v[98:99], v[48:49]
	v_pk_mul_f32 v[44:45], v[98:99], v[44:45]
	v_cvt_pk_bf16_f32 v52, v38, v39
	v_cvt_pk_bf16_f32 v53, v40, v41
	v_cvt_pk_bf16_f32 v54, v46, v47
	v_cvt_pk_bf16_f32 v55, v48, v49
	v_cvt_pk_bf16_f32 v56, v34, v35
	v_cvt_pk_bf16_f32 v57, v36, v37
	v_cvt_pk_bf16_f32 v58, v42, v43
	s_nop 0
	v_cvt_pk_bf16_f32 v59, v44, v45
	global_store_dwordx4 v[122:123], v[52:55], off offset:512
	global_store_dwordx4 v[122:123], v[56:59], off offset:576
	s_and_saveexec_b64 s[30:31], s[14:15]
	s_xor_b64 s[14:15], exec, s[30:31]
	s_cbranch_execnz .LBB0_568
	s_or_saveexec_b64 s[14:15], s[14:15]
	v_mov_b64_e32 v[70:71], s[28:29]
	s_xor_b64 exec, exec, s[14:15]
	s_cbranch_execnz .LBB0_569

.LBB0_558:
	v_and_b32_e32 v73, 0xffff0000, v27
	v_lshlrev_b32_e32 v27, 16, v27
	v_mov_b64_e32 v[30:31], v[148:149]
	v_mov_b64_e32 v[32:33], v[150:151]
	v_mov_b64_e32 v[34:35], v[152:153]
	v_mov_b64_e32 v[36:37], v[154:155]
	v_mov_b64_e32 v[50:51], v[156:157]
	v_mov_b64_e32 v[52:53], v[158:159]
	v_mov_b64_e32 v[58:59], v[160:161]
	v_mov_b64_e32 v[60:61], v[162:163]
	v_mov_b64_e32 v[54:55], v[164:165]
	v_mov_b64_e32 v[56:57], v[166:167]
	v_mov_b64_e32 v[66:67], v[168:169]
	v_mov_b64_e32 v[68:69], v[170:171]
	v_mov_b64_e32 v[42:43], v[172:173]
	v_mov_b64_e32 v[44:45], v[174:175]
	v_mov_b64_e32 v[62:63], v[176:177]
	v_mov_b64_e32 v[64:65], v[178:179]
	v_mov_b64_e32 v[38:39], v[180:181]
	v_mov_b64_e32 v[40:41], v[182:183]
	v_mov_b64_e32 v[46:47], v[184:185]
	v_mov_b64_e32 v[48:49], v[186:187]
	v_and_b32_e32 v74, 0xffff0000, v26
	v_lshlrev_b32_e32 v26, 16, v26
	v_and_b32_e32 v72, 0xffff0000, v28
	v_and_b32_e32 v0, 0xffff0000, v29
	v_lshlrev_b32_e32 v29, 16, v29
	v_lshlrev_b32_e32 v28, 16, v28
	v_lshlrev_b32_e32 v115, 16, v24
	v_and_b32_e32 v117, 0xffff0000, v24
	v_lshlrev_b32_e32 v119, 16, v25
	v_and_b32_e32 v121, 0xffff0000, v25
	v_lshlrev_b32_e32 v24, 16, v15
	v_and_b32_e32 v25, 0xffff0000, v15
	v_lshlrev_b32_e32 v76, 16, v19
	v_and_b32_e32 v77, 0xffff0000, v19
	v_and_b32_e32 v19, 0xffff0000, v16
	v_lshlrev_b32_e32 v78, 16, v20
	v_and_b32_e32 v79, 0xffff0000, v20
	v_lshlrev_b32_e32 v80, 16, v21
	v_and_b32_e32 v81, 0xffff0000, v21
	v_lshlrev_b32_e32 v20, 16, v17
	v_and_b32_e32 v21, 0xffff0000, v17
	v_fma_f32 v146, v51, v72, v31
	v_fma_f32 v122, v58, v26, v34
	v_fma_f32 v123, v59, v74, v35
	v_fma_f32 v124, v60, v27, v36
	v_lshlrev_b32_e32 v26, 16, v22
	v_and_b32_e32 v27, 0xffff0000, v22
	v_fma_f32 v125, v61, v73, v37
	v_fmac_f32_e32 v122, v66, v26
	v_fmac_f32_e32 v123, v67, v27
	v_lshlrev_b32_e32 v72, 16, v18
	v_and_b32_e32 v73, 0xffff0000, v18
	v_mad_u64_u32 v[74:75], s[14:15], v70, 3, 0
	v_fma_f32 v145, v50, v28, v30
	v_fma_f32 v147, v52, v29, v32
	v_lshlrev_b32_e32 v28, 16, v23
	v_and_b32_e32 v29, 0xffff0000, v23
	v_fmac_f32_e32 v122, v62, v72
	v_fmac_f32_e32 v123, v63, v73
	v_lshlrev_b32_e32 v22, 16, v14
	v_and_b32_e32 v23, 0xffff0000, v14
	v_mov_b32_e32 v14, v75
	v_fmac_f32_e32 v122, v46, v22
	v_fmac_f32_e32 v123, v47, v23
	v_mad_u64_u32 v[14:15], s[14:15], v71, 3, v[14:15]
	v_mov_b32_e32 v75, v14
	v_mul_f32_e32 v14, 0xbfb8aa3b, v122
	v_mul_f32_e32 v15, 0xbfb8aa3b, v123
	v_exp_f32_e32 v14, v14
	v_exp_f32_e32 v15, v15
	v_fmac_f32_e32 v124, v68, v28
	v_fmac_f32_e32 v125, v69, v29
	v_add_f32_e32 v14, 1.0, v14
	v_add_f32_e32 v15, 1.0, v15
	v_rcp_f32_e32 v14, v14
	v_rcp_f32_e32 v15, v15
	v_fmac_f32_e32 v124, v64, v76
	v_fmac_f32_e32 v125, v65, v77
	v_fmac_f32_e32 v124, v48, v24
	v_fmac_f32_e32 v125, v49, v25
	v_mul_f32_e32 v14, v122, v14
	v_mul_f32_e32 v15, v123, v15
	v_lshlrev_b32_e32 v18, 16, v16
	v_cvt_pk_bf16_f32 v14, v14, v15
	v_mul_f32_e32 v15, 0xbfb8aa3b, v124
	v_mul_f32_e32 v16, 0xbfb8aa3b, v125
	v_exp_f32_e32 v15, v15
	v_exp_f32_e32 v16, v16
	v_fmac_f32_e32 v145, v54, v115
	v_fmac_f32_e32 v146, v55, v117
	v_add_f32_e32 v15, 1.0, v15
	v_add_f32_e32 v16, 1.0, v16
	v_rcp_f32_e32 v15, v15
	v_rcp_f32_e32 v16, v16
	v_fmac_f32_e32 v145, v42, v78
	v_fmac_f32_e32 v146, v43, v79
	v_fmac_f32_e32 v145, v38, v18
	v_fmac_f32_e32 v146, v39, v19
	v_mul_f32_e32 v15, v124, v15
	v_mul_f32_e32 v16, v125, v16
	v_cvt_pk_bf16_f32 v15, v15, v16
	v_mul_f32_e32 v16, 0xbfb8aa3b, v145
	v_mul_f32_e32 v17, 0xbfb8aa3b, v146
	v_exp_f32_e32 v16, v16
	v_exp_f32_e32 v17, v17
	v_fma_f32 v0, v53, v0, v33
	v_fmac_f32_e32 v0, v57, v121
	v_add_f32_e32 v16, 1.0, v16
	v_add_f32_e32 v17, 1.0, v17
	v_fmac_f32_e32 v0, v45, v81
	v_rcp_f32_e32 v16, v16
	v_rcp_f32_e32 v17, v17
	v_fmac_f32_e32 v0, v41, v21
	v_fmac_f32_e32 v147, v56, v119
	v_mul_f32_e32 v70, 0xbfb8aa3b, v0
	v_fmac_f32_e32 v147, v44, v80
	v_exp_f32_e32 v70, v70
	v_fmac_f32_e32 v147, v40, v20
	v_mul_f32_e32 v16, v145, v16
	v_mul_f32_e32 v17, v146, v17
	v_cvt_pk_bf16_f32 v16, v16, v17
	v_mul_f32_e32 v17, 0xbfb8aa3b, v147
	v_exp_f32_e32 v17, v17
	v_add_f32_e32 v70, 1.0, v70
	v_rcp_f32_e32 v70, v70
	s_movk_i32 s14, 0x1ffc
	v_add_f32_e32 v17, 1.0, v17
	v_rcp_f32_e32 v17, v17
	v_mul_f32_e32 v0, v0, v70
	v_add_u32_e32 v70, s33, v126
	v_ashrrev_i32_e32 v71, 31, v70
	v_lshlrev_b64 v[70:71], 11, v[70:71]
	v_mul_f32_e32 v17, v147, v17
	v_lshl_add_u64 v[70:71], v[102:103], 0, v[70:71]
	v_cmp_lt_i32_e32 vcc, s14, v113
	v_cvt_pk_bf16_f32 v17, v17, v0
	global_store_dwordx4 v[70:71], v[14:17], off
	s_and_saveexec_b64 s[14:15], vcc
	s_cbranch_execz .LBB0_560
	v_add_u32_e32 v0, 0xffffe003, v113
	v_lshl_add_u64 v[14:15], v[74:75], 0, v[0:1]
	v_lshlrev_b64 v[14:15], 12, v[14:15]
	v_lshl_add_u64 v[14:15], v[104:105], 0, v[14:15]
	global_store_dwordx4 v[14:15], v[18:21], off offset:16
	global_store_dwordx4 v[14:15], v[22:25], off

	.amdhsa_kernel _Z4mega6Paramsii
		.amdhsa_group_segment_fixed_size 0
		.amdhsa_private_segment_fixed_size 0
		.amdhsa_kernarg_size 496
		.amdhsa_user_sgpr_count 2
		.amdhsa_user_sgpr_dispatch_ptr 0
		.amdhsa_user_sgpr_queue_ptr 0
		.amdhsa_user_sgpr_kernarg_segment_ptr 1
		.amdhsa_user_sgpr_dispatch_id 0
		.amdhsa_user_sgpr_kernarg_preload_length 0
		.amdhsa_user_sgpr_kernarg_preload_offset 0
		.amdhsa_user_sgpr_private_segment_size 0
		.amdhsa_uses_dynamic_stack 0
		.amdhsa_enable_private_segment 0
		.amdhsa_system_sgpr_workgroup_id_x 1
		.amdhsa_system_sgpr_workgroup_id_y 0
		.amdhsa_system_sgpr_workgroup_id_z 0
		.amdhsa_system_sgpr_workgroup_info 0
		.amdhsa_system_vgpr_workitem_id 2
		.amdhsa_next_free_vgpr 256
		.amdhsa_next_free_sgpr 102
		.amdhsa_accum_offset 256
		.amdhsa_reserve_vcc 1
		.amdhsa_float_round_mode_32 0
		.amdhsa_float_round_mode_16_64 0
		.amdhsa_float_denorm_mode_32 3
		.amdhsa_float_denorm_mode_16_64 3
		.amdhsa_dx10_clamp 1
		.amdhsa_ieee_mode 1
		.amdhsa_fp16_overflow 0
		.amdhsa_tg_split 0
		.amdhsa_exception_fp_ieee_invalid_op 0
		.amdhsa_exception_fp_denorm_src 0
		.amdhsa_exception_fp_ieee_div_zero 0
		.amdhsa_exception_fp_ieee_overflow 0
		.amdhsa_exception_fp_ieee_underflow 0
		.amdhsa_exception_fp_ieee_inexact 0
		.amdhsa_exception_int_div_zero 0
	.end_amdhsa_kernel

amdhsa.kernels:
  - .agpr_count:     0
    .args:
      - .offset:         0
        .size:           232
        .value_kind:     by_value
      - .offset:         232
        .size:           4
        .value_kind:     by_value
      - .offset:         236
        .size:           4
        .value_kind:     by_value
      - .offset:         240
        .size:           4
        .value_kind:     hidden_block_count_x
      - .offset:         244
        .size:           4
        .value_kind:     hidden_block_count_y
      - .offset:         248
        .size:           4
        .value_kind:     hidden_block_count_z
      - .offset:         252
        .size:           2
        .value_kind:     hidden_group_size_x
      - .offset:         254
        .size:           2
        .value_kind:     hidden_group_size_y
      - .offset:         256
        .size:           2
        .value_kind:     hidden_group_size_z
      - .offset:         258
        .size:           2
        .value_kind:     hidden_remainder_x
      - .offset:         260
        .size:           2
        .value_kind:     hidden_remainder_y
      - .offset:         262
        .size:           2
        .value_kind:     hidden_remainder_z
      - .offset:         280
        .size:           8
        .value_kind:     hidden_global_offset_x
      - .offset:         288
        .size:           8
        .value_kind:     hidden_global_offset_y
      - .offset:         296
        .size:           8
        .value_kind:     hidden_global_offset_z
      - .offset:         304
        .size:           2
        .value_kind:     hidden_grid_dims
      - .offset:         328
        .size:           8
        .value_kind:     hidden_multigrid_sync_arg
      - .offset:         360
        .size:           4
        .value_kind:     hidden_dynamic_lds_size
    .group_segment_fixed_size: 0
    .kernarg_segment_align: 8
    .kernarg_segment_size: 496
    .language:       OpenCL C
    .language_version:
      - 2
      - 0
    .max_flat_workgroup_size: 512
    .name:           _Z4mega6Paramsii
    .private_segment_fixed_size: 0
    .sgpr_count:     108
    .sgpr_spill_count: 307
    .symbol:         _Z4mega6Paramsii.kd
    .uniform_work_group_size: 1
    .uses_dynamic_stack: false
    .vgpr_count:     256
    .vgpr_spill_count: 0
    .wavefront_size: 64
